# P1 epilogue stores spread over next tile K-loop + WGM4 tile order P1/P6 + v_mov_b64 accumulator zeroing
# baseline (speedup 1.0000x reference)
.LBB0_113:
	s_lshl_b32 s6, s6, 5
	s_and_b32 s18, s6, 0x60
	s_mov_b64 s[6:7], 0x80
	s_add_i32 m0, s51, 0x18000
	v_lshl_add_u64 v[6:7], v[6:7], 0, s[6:7]
	s_lshl_b32 s9, s8, 13
	s_lshl_b32 s19, s18, 7
	s_waitcnt vmcnt(2)
	s_barrier
	global_load_lds_dwordx4 v[6:7], off
	v_lshl_add_u64 v[4:5], v[4:5], 0, s[6:7]
	s_add_i32 m0, s51, 0x1a000
	s_add_i32 s77, s51, 0x8000
	s_add_i32 s78, s51, 0xa000
	global_load_lds_dwordx4 v[4:5], off
	v_lshl_add_u64 v[0:1], v[0:1], 0, s[6:7]
	s_mov_b32 m0, s77
	s_add_u32 s16, s56, 0x40080
	global_load_lds_dwordx4 v[0:1], off
	v_lshl_add_u64 v[0:1], v[2:3], 0, s[6:7]
	s_mov_b32 m0, s78
	s_addc_u32 s17, s57, 0
	global_load_lds_dwordx4 v[0:1], off
	s_add_i32 m0, s51, 0x1c000
	v_lshl_add_u64 v[0:1], s[16:17], 0, v[132:133]
	global_load_lds_dwordx4 v[0:1], off
	v_lshl_add_u64 v[0:1], s[16:17], 0, v[128:129]
	s_add_i32 m0, s51, 0x1e000
	s_cmpk_lt_u32 s1, 0x100
	global_load_lds_dwordx4 v[0:1], off
	v_lshrrev_b32_e32 v1, 1, v9
	v_and_b32_e32 v1, 24, v1
	v_and_b32_e32 v0, 15, v9
	v_lshlrev_b32_e32 v2, 1, v1
	v_lshl_or_b32 v144, s8, 6, v0
	v_lshl_or_b32 v0, v0, 6, v2
	v_lshlrev_b32_e32 v2, 2, v9
	v_and_b32_e32 v2, 32, v2
	v_bitop3_b32 v3, v0, s9, v2 bitop3:0xde
	v_bitop3_b32 v145, v0, s19, v2 bitop3:0xde
	v_lshlrev_b32_e32 v0, 14, v13
	v_and_b32_e32 v0, 0xffff8000, v0
	v_or_b32_e32 v146, s18, v1
	v_lshl_add_u32 v0, v12, 11, v0
	v_and_b32_e32 v1, 1, v13
	v_lshl_or_b32 v0, v1, 6, v0
	v_lshl_add_u32 v136, v14, 1, v0
	v_lshlrev_b32_e32 v0, 14, v8
	v_and_b32_e32 v0, 0xffff8000, v0
	s_waitcnt vmcnt(6)
	v_lshl_add_u32 v0, v10, 11, v0
	v_and_b32_e32 v1, 1, v8
	s_cselect_b64 s[8:9], -1, 0
	v_lshl_or_b32 v0, v1, 6, v0
	s_add_i32 s81, 0, 0x10000
	s_add_i32 s82, 0, 0x14000
	s_sext_i32_i8 s84, s0
	s_ashr_i32 s79, s34, 31
	s_mov_b32 s80, s34
	v_mov_b32_e32 v137, v133
	v_lshl_add_u32 v138, v11, 1, v0
	v_mov_b32_e32 v139, v133
	v_mov_b64_e32 v[140:141], 0xb00
	v_mov_b64_e32 v[142:143], 0xaff
	v_add_u32_e32 v147, s81, v145
	v_add_u32_e32 v148, s82, v145
	v_add_u32_e32 v149, 0, v3
	s_movk_i32 s83, 0x1600
	v_mul_u32_u24_e32 v255, 0x1600, v144
	v_lshl_add_u32 v255, v146, 1, v255
	s_mul_i32 s98, s50, 0x160000
	s_lshl_b32 s101, s84, 8
	s_add_u32 s98, s98, s101
	s_addc_u32 s99, 0, 0
	s_add_u32 s98, s98, s26
	s_addc_u32 s99, s99, s27
	s_barrier
	s_branch .LBB0_116

.LBB0_118:
	s_ashr_i32 s19, s18, 31
	s_lshl_b64 s[20:21], s[18:19], 19
	s_add_u32 s22, s24, s20
	s_addc_u32 s23, s25, s21
	s_and_b64 s[20:21], s[0:1], exec
	s_cselect_b32 s19, s23, s55
	s_cselect_b32 s85, s22, s54
	s_ashr_i32 s17, s16, 31
	s_lshl_b64 s[20:21], s[16:17], 19
	s_add_u32 s48, s14, s20
	s_addc_u32 s49, s15, s21
	s_and_b64 s[20:21], s[0:1], exec
	s_cselect_b32 s17, s49, s57
	s_cselect_b32 s86, s48, s56
	s_add_u32 s54, s54, 0x40080
	s_addc_u32 s55, s55, 0
	s_add_u32 s87, s56, 0x100
	v_mov_b32_e32 v0, 0
	s_addc_u32 s88, s57, 0
	s_mov_b32 s89, -2
	v_mov_b32_e32 v1, 0
	v_mov_b64_e32 v[2:3], 0
	v_mov_b64_e32 v[4:5], 0
	v_mov_b64_e32 v[6:7], 0
	v_mov_b64_e32 v[8:9], 0
	v_mov_b64_e32 v[10:11], 0
	v_mov_b64_e32 v[12:13], 0
	v_mov_b64_e32 v[14:15], 0
	v_mov_b64_e32 v[16:17], 0
	v_mov_b64_e32 v[18:19], 0
	v_mov_b64_e32 v[20:21], 0
	v_mov_b64_e32 v[22:23], 0
	v_mov_b64_e32 v[24:25], 0
	v_mov_b64_e32 v[26:27], 0
	v_mov_b64_e32 v[28:29], 0
	v_mov_b64_e32 v[30:31], 0
	v_mov_b64_e32 v[32:33], 0
	v_mov_b64_e32 v[34:35], 0
	v_mov_b64_e32 v[36:37], 0
	v_mov_b64_e32 v[38:39], 0
	v_mov_b64_e32 v[40:41], 0
	v_mov_b64_e32 v[42:43], 0
	v_mov_b64_e32 v[44:45], 0
	v_mov_b64_e32 v[46:47], 0
	v_mov_b64_e32 v[48:49], 0
	v_mov_b64_e32 v[50:51], 0
	v_mov_b64_e32 v[52:53], 0
	v_mov_b64_e32 v[54:55], 0
	v_mov_b64_e32 v[56:57], 0
	v_mov_b64_e32 v[58:59], 0
	v_mov_b64_e32 v[60:61], 0
	v_mov_b64_e32 v[62:63], 0
	v_mov_b64_e32 v[64:65], 0
	v_mov_b64_e32 v[66:67], 0
	v_mov_b64_e32 v[68:69], 0
	v_mov_b64_e32 v[70:71], 0
	v_mov_b64_e32 v[72:73], 0
	v_mov_b64_e32 v[74:75], 0
	v_mov_b64_e32 v[76:77], 0
	v_mov_b64_e32 v[78:79], 0
	v_mov_b64_e32 v[80:81], 0
	v_mov_b64_e32 v[82:83], 0
	v_mov_b64_e32 v[84:85], 0
	v_mov_b64_e32 v[86:87], 0
	v_mov_b64_e32 v[88:89], 0
	v_mov_b64_e32 v[90:91], 0
	v_mov_b64_e32 v[92:93], 0
	v_mov_b64_e32 v[94:95], 0
	v_mov_b64_e32 v[96:97], 0
	v_mov_b64_e32 v[98:99], 0
	v_mov_b64_e32 v[100:101], 0
	v_mov_b64_e32 v[102:103], 0
	v_mov_b64_e32 v[104:105], 0
	v_mov_b64_e32 v[106:107], 0
	v_mov_b64_e32 v[108:109], 0
	v_mov_b64_e32 v[110:111], 0
	v_mov_b64_e32 v[112:113], 0
	v_mov_b64_e32 v[114:115], 0
	v_mov_b64_e32 v[116:117], 0
	v_mov_b64_e32 v[118:119], 0
	v_mov_b64_e32 v[120:121], 0
	v_mov_b64_e32 v[122:123], 0
	v_mov_b64_e32 v[124:125], 0
	v_mov_b64_e32 v[126:127], 0
.LBB0_119:
	s_cmp_lt_i32 s89, 6
	s_cbranch_scc0 .Lsp1_hi
	s_cmp_lt_i32 s89, 2
	s_cbranch_scc0 .Lsp1_23
	s_cmp_lt_i32 s89, 0
	s_cbranch_scc0 .Lsp1_1
	global_store_dwordx4 v255, v[224:227], s[98:99]
	s_branch .Lsp1_done
.Lsp1_1:
	global_store_dwordx4 v255, v[228:231], s[98:99]
	s_branch .Lsp1_done
.Lsp1_23:
	s_cmp_lt_i32 s89, 4
	s_cbranch_scc0 .Lsp1_3
	global_store_dwordx4 v255, v[232:235], s[98:99]
	s_branch .Lsp1_done
.Lsp1_3:
	global_store_dwordx4 v255, v[236:239], s[98:99]
	s_branch .Lsp1_done
.Lsp1_hi:
	s_cmp_lt_i32 s89, 10
	s_cbranch_scc0 .Lsp1_67
	s_cmp_lt_i32 s89, 8
	s_cbranch_scc0 .Lsp1_5
	global_store_dwordx4 v255, v[244:247], s[98:99]
	s_branch .Lsp1_done
.Lsp1_5:
	global_store_dwordx4 v255, v[248:251], s[98:99]
	s_branch .Lsp1_done
.Lsp1_67:
	s_cmp_lt_i32 s89, 12
	s_cbranch_scc0 .Lsp1_7
	global_store_dwordx4 v255, v[216:219], s[98:99]
	s_branch .Lsp1_done
.Lsp1_7:
	global_store_dwordx4 v255, v[220:223], s[98:99]
.Lsp1_done:
	s_mov_b32 s101, 0x16000
	s_cmp_eq_u32 s89, 4
	s_cselect_b32 s101, 0x6e000, s101
	s_add_u32 s98, s98, s101
	s_addc_u32 s99, s99, 0
	ds_read_b128 v[150:153], v147
	ds_read_b128 v[154:157], v147 offset:1024
	ds_read_b128 v[158:161], v147 offset:2048
	ds_read_b128 v[162:165], v147 offset:3072
	ds_read_b128 v[166:169], v148
	ds_read_b128 v[170:173], v148 offset:1024
	ds_read_b128 v[174:177], v148 offset:2048
	ds_read_b128 v[178:181], v148 offset:3072
	s_add_u32 s20, s54, 0xfffc0080
	s_addc_u32 s21, s55, -1
	s_cmp_eq_u32 s89, 12
	s_cselect_b32 s59, s19, s21
	s_cselect_b32 s58, s85, s20
	s_cselect_b32 s57, s17, s88
	s_cselect_b32 s56, s86, s87
	v_lshl_add_u64 v[214:215], s[54:55], 0, v[136:137]
	s_add_i32 m0, s51, 0xc000
	ds_read_b128 v[182:185], v149
	ds_read_b128 v[186:189], v149 offset:1024
	ds_read_b128 v[190:193], v149 offset:2048
	ds_read_b128 v[194:197], v149 offset:3072
	ds_read_b128 v[198:201], v149 offset:4096
	ds_read_b128 v[202:205], v149 offset:5120
	ds_read_b128 v[206:209], v149 offset:6144
	ds_read_b128 v[210:213], v149 offset:7168
	global_load_lds_dwordx4 v[214:215], off
	v_lshl_add_u64 v[214:215], s[54:55], 0, v[138:139]
	s_add_i32 m0, s51, 0xe000
	s_nop 0
	global_load_lds_dwordx4 v[214:215], off
	s_waitcnt vmcnt(9)
	s_waitcnt lgkmcnt(0)
	s_barrier
	s_setprio 1
	s_waitcnt lgkmcnt(0)
	v_mfma_f32_16x16x32_bf16 v[124:127], v[150:153], v[182:185], v[124:127]
	v_mfma_f32_16x16x32_bf16 v[116:119], v[158:161], v[182:185], v[116:119]
	v_mfma_f32_16x16x32_bf16 v[108:111], v[150:153], v[190:193], v[108:111]
	v_mfma_f32_16x16x32_bf16 v[100:103], v[158:161], v[190:193], v[100:103]
	v_mfma_f32_16x16x32_bf16 v[92:95], v[150:153], v[198:201], v[92:95]
	v_mfma_f32_16x16x32_bf16 v[84:87], v[158:161], v[198:201], v[84:87]
	v_mfma_f32_16x16x32_bf16 v[76:79], v[150:153], v[206:209], v[76:79]
	v_mfma_f32_16x16x32_bf16 v[68:71], v[158:161], v[206:209], v[68:71]
	v_mfma_f32_16x16x32_bf16 v[124:127], v[154:157], v[186:189], v[124:127]
	v_mfma_f32_16x16x32_bf16 v[116:119], v[162:165], v[186:189], v[116:119]
	v_mfma_f32_16x16x32_bf16 v[108:111], v[154:157], v[194:197], v[108:111]
	v_mfma_f32_16x16x32_bf16 v[100:103], v[162:165], v[194:197], v[100:103]
	v_mfma_f32_16x16x32_bf16 v[92:95], v[154:157], v[202:205], v[92:95]
	v_mfma_f32_16x16x32_bf16 v[84:87], v[162:165], v[202:205], v[84:87]
	v_mfma_f32_16x16x32_bf16 v[76:79], v[154:157], v[210:213], v[76:79]
	v_mfma_f32_16x16x32_bf16 v[68:71], v[162:165], v[210:213], v[68:71]
	s_setprio 0
	s_setprio 1
	v_mfma_f32_16x16x32_bf16 v[120:123], v[166:169], v[182:185], v[120:123]
	v_mfma_f32_16x16x32_bf16 v[112:115], v[174:177], v[182:185], v[112:115]
	v_mfma_f32_16x16x32_bf16 v[104:107], v[166:169], v[190:193], v[104:107]
	v_mfma_f32_16x16x32_bf16 v[96:99], v[174:177], v[190:193], v[96:99]
	v_mfma_f32_16x16x32_bf16 v[88:91], v[166:169], v[198:201], v[88:91]
	v_mfma_f32_16x16x32_bf16 v[80:83], v[174:177], v[198:201], v[80:83]
	v_mfma_f32_16x16x32_bf16 v[72:75], v[166:169], v[206:209], v[72:75]
	v_mfma_f32_16x16x32_bf16 v[64:67], v[174:177], v[206:209], v[64:67]
	v_mfma_f32_16x16x32_bf16 v[120:123], v[170:173], v[186:189], v[120:123]
	v_mfma_f32_16x16x32_bf16 v[112:115], v[178:181], v[186:189], v[112:115]
	v_mfma_f32_16x16x32_bf16 v[104:107], v[170:173], v[194:197], v[104:107]
	v_mfma_f32_16x16x32_bf16 v[96:99], v[178:181], v[194:197], v[96:99]
	v_mfma_f32_16x16x32_bf16 v[88:91], v[170:173], v[202:205], v[88:91]
	v_mfma_f32_16x16x32_bf16 v[80:83], v[178:181], v[202:205], v[80:83]
	v_mfma_f32_16x16x32_bf16 v[72:75], v[170:173], v[210:213], v[72:75]
	v_mfma_f32_16x16x32_bf16 v[64:67], v[178:181], v[210:213], v[64:67]
	s_setprio 0
	s_barrier
	s_add_i32 s20, s81, s60
	v_lshl_add_u64 v[214:215], s[56:57], 0, v[132:133]
	s_mov_b32 m0, s20
	ds_read_b128 v[182:185], v149 offset:16384
	ds_read_b128 v[186:189], v149 offset:17408
	ds_read_b128 v[190:193], v149 offset:18432
	ds_read_b128 v[194:197], v149 offset:19456
	ds_read_b128 v[198:201], v149 offset:20480
	ds_read_b128 v[202:205], v149 offset:21504
	ds_read_b128 v[206:209], v149 offset:22528
	ds_read_b128 v[210:213], v149 offset:23552
	global_load_lds_dwordx4 v[214:215], off
	s_add_i32 m0, s20, 0x2000
	s_add_u32 s20, s56, 0x40000
	v_lshl_add_u64 v[252:253], s[56:57], 0, v[128:129]
	s_addc_u32 s21, s57, 0
	s_add_i32 s33, s82, s60
	global_load_lds_dwordx4 v[252:253], off
	v_lshl_add_u64 v[214:215], s[20:21], 0, v[132:133]
	s_mov_b32 m0, s33
	v_lshl_add_u64 v[252:253], s[58:59], 0, v[130:131]
	global_load_lds_dwordx4 v[214:215], off
	v_lshl_add_u64 v[214:215], s[20:21], 0, v[128:129]
	s_add_i32 m0, s33, 0x2000
	s_nop 0
	global_load_lds_dwordx4 v[214:215], off
	v_lshl_add_u64 v[214:215], s[58:59], 0, v[134:135]
	s_mov_b32 m0, s51
	s_nop 0
	global_load_lds_dwordx4 v[214:215], off
	s_mov_b32 m0, s63
	s_nop 0
	global_load_lds_dwordx4 v[252:253], off
	s_waitcnt vmcnt(9)
	s_waitcnt lgkmcnt(0)
	s_barrier
	s_setprio 1
	s_waitcnt lgkmcnt(0)
	v_mfma_f32_16x16x32_bf16 v[60:63], v[150:153], v[182:185], v[60:63]
	v_mfma_f32_16x16x32_bf16 v[52:55], v[158:161], v[182:185], v[52:55]
	v_mfma_f32_16x16x32_bf16 v[44:47], v[150:153], v[190:193], v[44:47]
	v_mfma_f32_16x16x32_bf16 v[36:39], v[158:161], v[190:193], v[36:39]
	v_mfma_f32_16x16x32_bf16 v[28:31], v[150:153], v[198:201], v[28:31]
	v_mfma_f32_16x16x32_bf16 v[20:23], v[158:161], v[198:201], v[20:23]
	v_mfma_f32_16x16x32_bf16 v[12:15], v[150:153], v[206:209], v[12:15]
	v_mfma_f32_16x16x32_bf16 v[4:7], v[158:161], v[206:209], v[4:7]
	v_mfma_f32_16x16x32_bf16 v[60:63], v[154:157], v[186:189], v[60:63]
	v_mfma_f32_16x16x32_bf16 v[52:55], v[162:165], v[186:189], v[52:55]
	v_mfma_f32_16x16x32_bf16 v[44:47], v[154:157], v[194:197], v[44:47]
	v_mfma_f32_16x16x32_bf16 v[36:39], v[162:165], v[194:197], v[36:39]
	v_mfma_f32_16x16x32_bf16 v[28:31], v[154:157], v[202:205], v[28:31]
	v_mfma_f32_16x16x32_bf16 v[20:23], v[162:165], v[202:205], v[20:23]
	v_mfma_f32_16x16x32_bf16 v[12:15], v[154:157], v[210:213], v[12:15]
	v_mfma_f32_16x16x32_bf16 v[4:7], v[162:165], v[210:213], v[4:7]
	s_setprio 0
	s_setprio 1
	v_mfma_f32_16x16x32_bf16 v[56:59], v[166:169], v[182:185], v[56:59]
	v_mfma_f32_16x16x32_bf16 v[48:51], v[174:177], v[182:185], v[48:51]
	v_mfma_f32_16x16x32_bf16 v[40:43], v[166:169], v[190:193], v[40:43]
	v_mfma_f32_16x16x32_bf16 v[32:35], v[174:177], v[190:193], v[32:35]
	v_mfma_f32_16x16x32_bf16 v[24:27], v[166:169], v[198:201], v[24:27]
	v_mfma_f32_16x16x32_bf16 v[16:19], v[174:177], v[198:201], v[16:19]
	v_mfma_f32_16x16x32_bf16 v[8:11], v[166:169], v[206:209], v[8:11]
	v_mfma_f32_16x16x32_bf16 v[0:3], v[174:177], v[206:209], v[0:3]
	v_mfma_f32_16x16x32_bf16 v[56:59], v[170:173], v[186:189], v[56:59]
	v_mfma_f32_16x16x32_bf16 v[48:51], v[178:181], v[186:189], v[48:51]
	v_mfma_f32_16x16x32_bf16 v[40:43], v[170:173], v[194:197], v[40:43]
	v_mfma_f32_16x16x32_bf16 v[32:35], v[178:181], v[194:197], v[32:35]
	v_mfma_f32_16x16x32_bf16 v[24:27], v[170:173], v[202:205], v[24:27]
	v_mfma_f32_16x16x32_bf16 v[16:19], v[178:181], v[202:205], v[16:19]
	v_mfma_f32_16x16x32_bf16 v[8:11], v[170:173], v[210:213], v[8:11]
	v_mfma_f32_16x16x32_bf16 v[0:3], v[178:181], v[210:213], v[0:3]
	s_setprio 0
	s_barrier
	s_add_i32 s33, 0, 0x18000
	s_add_i32 s75, 0, 0x1c000
	v_add_u32_e32 v162, s33, v145
	v_add_u32_e32 v178, s75, v145
	ds_read_b128 v[150:153], v162
	ds_read_b128 v[154:157], v162 offset:1024
	ds_read_b128 v[158:161], v162 offset:2048
	ds_read_b128 v[162:165], v162 offset:3072
	ds_read_b128 v[166:169], v178
	ds_read_b128 v[170:173], v178 offset:1024
	ds_read_b128 v[174:177], v178 offset:2048
	ds_read_b128 v[178:181], v178 offset:3072
	s_add_u32 s20, s58, 0x40000
	s_addc_u32 s21, s59, 0
	s_mov_b32 m0, s64
	v_lshl_add_u64 v[214:215], s[20:21], 0, v[134:135]
	ds_read_b128 v[182:185], v149 offset:32768
	ds_read_b128 v[186:189], v149 offset:33792
	ds_read_b128 v[190:193], v149 offset:34816
	ds_read_b128 v[194:197], v149 offset:35840
	ds_read_b128 v[198:201], v149 offset:36864
	ds_read_b128 v[202:205], v149 offset:37888
	ds_read_b128 v[206:209], v149 offset:38912
	ds_read_b128 v[210:213], v149 offset:39936
	global_load_lds_dwordx4 v[214:215], off
	v_lshl_add_u64 v[214:215], s[20:21], 0, v[130:131]
	s_mov_b32 m0, s65
	s_nop 0
	global_load_lds_dwordx4 v[214:215], off
	s_waitcnt vmcnt(8)
	s_waitcnt lgkmcnt(0)
	s_barrier
	s_setprio 1
	s_waitcnt lgkmcnt(0)
	v_mfma_f32_16x16x32_bf16 v[124:127], v[150:153], v[182:185], v[124:127]
	v_mfma_f32_16x16x32_bf16 v[116:119], v[158:161], v[182:185], v[116:119]
	v_mfma_f32_16x16x32_bf16 v[108:111], v[150:153], v[190:193], v[108:111]
	v_mfma_f32_16x16x32_bf16 v[100:103], v[158:161], v[190:193], v[100:103]
	v_mfma_f32_16x16x32_bf16 v[92:95], v[150:153], v[198:201], v[92:95]
	v_mfma_f32_16x16x32_bf16 v[84:87], v[158:161], v[198:201], v[84:87]
	v_mfma_f32_16x16x32_bf16 v[76:79], v[150:153], v[206:209], v[76:79]
	v_mfma_f32_16x16x32_bf16 v[68:71], v[158:161], v[206:209], v[68:71]
	v_mfma_f32_16x16x32_bf16 v[124:127], v[154:157], v[186:189], v[124:127]
	v_mfma_f32_16x16x32_bf16 v[116:119], v[162:165], v[186:189], v[116:119]
	v_mfma_f32_16x16x32_bf16 v[108:111], v[154:157], v[194:197], v[108:111]
	v_mfma_f32_16x16x32_bf16 v[100:103], v[162:165], v[194:197], v[100:103]
	v_mfma_f32_16x16x32_bf16 v[92:95], v[154:157], v[202:205], v[92:95]
	v_mfma_f32_16x16x32_bf16 v[84:87], v[162:165], v[202:205], v[84:87]
	v_mfma_f32_16x16x32_bf16 v[76:79], v[154:157], v[210:213], v[76:79]
	v_mfma_f32_16x16x32_bf16 v[68:71], v[162:165], v[210:213], v[68:71]
	s_setprio 0
	s_setprio 1
	v_mfma_f32_16x16x32_bf16 v[120:123], v[166:169], v[182:185], v[120:123]
	v_mfma_f32_16x16x32_bf16 v[112:115], v[174:177], v[182:185], v[112:115]
	v_mfma_f32_16x16x32_bf16 v[104:107], v[166:169], v[190:193], v[104:107]
	v_mfma_f32_16x16x32_bf16 v[96:99], v[174:177], v[190:193], v[96:99]
	v_mfma_f32_16x16x32_bf16 v[88:91], v[166:169], v[198:201], v[88:91]
	v_mfma_f32_16x16x32_bf16 v[80:83], v[174:177], v[198:201], v[80:83]
	v_mfma_f32_16x16x32_bf16 v[72:75], v[166:169], v[206:209], v[72:75]
	v_mfma_f32_16x16x32_bf16 v[64:67], v[174:177], v[206:209], v[64:67]
	v_mfma_f32_16x16x32_bf16 v[120:123], v[170:173], v[186:189], v[120:123]
	v_mfma_f32_16x16x32_bf16 v[112:115], v[178:181], v[186:189], v[112:115]
	v_mfma_f32_16x16x32_bf16 v[104:107], v[170:173], v[194:197], v[104:107]
	v_mfma_f32_16x16x32_bf16 v[96:99], v[178:181], v[194:197], v[96:99]
	v_mfma_f32_16x16x32_bf16 v[88:91], v[170:173], v[202:205], v[88:91]
	v_mfma_f32_16x16x32_bf16 v[80:83], v[178:181], v[202:205], v[80:83]
	v_mfma_f32_16x16x32_bf16 v[72:75], v[170:173], v[210:213], v[72:75]
	v_mfma_f32_16x16x32_bf16 v[64:67], v[178:181], v[210:213], v[64:67]
	s_setprio 0
	s_barrier
	s_add_i32 s20, s33, s60
	s_add_u32 s94, s56, 0x80
	s_addc_u32 s95, s57, 0
	s_add_u32 s96, s58, 0x80
	s_addc_u32 s97, s59, 0
	v_lshl_add_u64 v[214:215], s[94:95], 0, v[132:133]
	s_mov_b32 m0, s20
	ds_read_b128 v[182:185], v149 offset:49152
	ds_read_b128 v[186:189], v149 offset:50176
	ds_read_b128 v[190:193], v149 offset:51200
	ds_read_b128 v[194:197], v149 offset:52224
	ds_read_b128 v[198:201], v149 offset:53248
	ds_read_b128 v[202:205], v149 offset:54272
	ds_read_b128 v[206:209], v149 offset:55296
	ds_read_b128 v[210:213], v149 offset:56320
	global_load_lds_dwordx4 v[214:215], off
	s_add_i32 m0, s20, 0x2000
	s_add_u32 s20, s56, 0x40080
	v_lshl_add_u64 v[214:215], s[94:95], 0, v[128:129]
	s_addc_u32 s21, s57, 0
	s_add_i32 s33, s75, s60
	global_load_lds_dwordx4 v[214:215], off
	v_lshl_add_u64 v[214:215], s[20:21], 0, v[132:133]
	s_mov_b32 m0, s33
	s_nop 0
	global_load_lds_dwordx4 v[214:215], off
	v_lshl_add_u64 v[214:215], s[20:21], 0, v[128:129]
	s_add_i32 m0, s33, 0x2000
	s_nop 0
	global_load_lds_dwordx4 v[214:215], off
	v_lshl_add_u64 v[214:215], s[96:97], 0, v[134:135]
	s_mov_b32 m0, s77
	s_nop 0
	global_load_lds_dwordx4 v[214:215], off
	v_lshl_add_u64 v[214:215], s[96:97], 0, v[130:131]
	s_mov_b32 m0, s78
	s_nop 0
	global_load_lds_dwordx4 v[214:215], off
	s_waitcnt vmcnt(8)
	s_waitcnt lgkmcnt(0)
	s_barrier
	s_setprio 1
	s_waitcnt lgkmcnt(0)
	v_mfma_f32_16x16x32_bf16 v[60:63], v[150:153], v[182:185], v[60:63]
	v_mfma_f32_16x16x32_bf16 v[52:55], v[158:161], v[182:185], v[52:55]
	v_mfma_f32_16x16x32_bf16 v[44:47], v[150:153], v[190:193], v[44:47]
	v_mfma_f32_16x16x32_bf16 v[36:39], v[158:161], v[190:193], v[36:39]
	v_mfma_f32_16x16x32_bf16 v[28:31], v[150:153], v[198:201], v[28:31]
	v_mfma_f32_16x16x32_bf16 v[20:23], v[158:161], v[198:201], v[20:23]
	v_mfma_f32_16x16x32_bf16 v[12:15], v[150:153], v[206:209], v[12:15]
	v_mfma_f32_16x16x32_bf16 v[4:7], v[158:161], v[206:209], v[4:7]
	v_mfma_f32_16x16x32_bf16 v[60:63], v[154:157], v[186:189], v[60:63]
	v_mfma_f32_16x16x32_bf16 v[52:55], v[162:165], v[186:189], v[52:55]
	v_mfma_f32_16x16x32_bf16 v[44:47], v[154:157], v[194:197], v[44:47]
	v_mfma_f32_16x16x32_bf16 v[36:39], v[162:165], v[194:197], v[36:39]
	v_mfma_f32_16x16x32_bf16 v[28:31], v[154:157], v[202:205], v[28:31]
	v_mfma_f32_16x16x32_bf16 v[20:23], v[162:165], v[202:205], v[20:23]
	v_mfma_f32_16x16x32_bf16 v[12:15], v[154:157], v[210:213], v[12:15]
	v_mfma_f32_16x16x32_bf16 v[4:7], v[162:165], v[210:213], v[4:7]
	s_setprio 0
	s_setprio 1
	v_mfma_f32_16x16x32_bf16 v[56:59], v[166:169], v[182:185], v[56:59]
	v_mfma_f32_16x16x32_bf16 v[48:51], v[174:177], v[182:185], v[48:51]
	v_mfma_f32_16x16x32_bf16 v[40:43], v[166:169], v[190:193], v[40:43]
	v_mfma_f32_16x16x32_bf16 v[32:35], v[174:177], v[190:193], v[32:35]
	v_mfma_f32_16x16x32_bf16 v[24:27], v[166:169], v[198:201], v[24:27]
	v_mfma_f32_16x16x32_bf16 v[16:19], v[174:177], v[198:201], v[16:19]
	v_mfma_f32_16x16x32_bf16 v[8:11], v[166:169], v[206:209], v[8:11]
	v_mfma_f32_16x16x32_bf16 v[0:3], v[174:177], v[206:209], v[0:3]
	v_mfma_f32_16x16x32_bf16 v[56:59], v[170:173], v[186:189], v[56:59]
	v_mfma_f32_16x16x32_bf16 v[48:51], v[178:181], v[186:189], v[48:51]
	v_mfma_f32_16x16x32_bf16 v[40:43], v[170:173], v[194:197], v[40:43]
	v_mfma_f32_16x16x32_bf16 v[32:35], v[178:181], v[194:197], v[32:35]
	v_mfma_f32_16x16x32_bf16 v[24:27], v[170:173], v[202:205], v[24:27]
	v_mfma_f32_16x16x32_bf16 v[16:19], v[178:181], v[202:205], v[16:19]
	v_mfma_f32_16x16x32_bf16 v[8:11], v[170:173], v[210:213], v[8:11]
	v_mfma_f32_16x16x32_bf16 v[0:3], v[178:181], v[210:213], v[0:3]
	s_setprio 0
	s_barrier
	s_add_i32 s89, s89, 2
	s_add_u32 s54, s54, 0x100
	s_addc_u32 s55, s55, 0
	s_add_u32 s87, s87, 0x100
	s_addc_u32 s88, s88, 0
	s_cmp_gt_u32 s89, 13
	s_cbranch_scc0 .LBB0_119
	s_and_b64 vcc, exec, s[8:9]
	s_cbranch_vccz .LBB0_122
	s_barrier
.LBB0_122:
	s_mul_i32 s98, s50, 0x160000
	s_lshl_b32 s101, s84, 8
	s_add_u32 s98, s98, s101
	s_addc_u32 s99, 0, 0
	s_add_u32 s98, s98, s26
	s_addc_u32 s99, s99, s27
	v_exp_f32_e32 v151, v124
	v_mul_f32_e32 v120, v124, v120
	v_exp_f32_e32 v154, v125
	v_mul_f32_e32 v121, v125, v121
	v_add_f32_e32 v151, 1.0, v151
	v_rcp_f32_e32 v151, v151
	v_add_f32_e32 v124, 1.0, v154
	v_rcp_f32_e32 v124, v124
	v_mul_f32_e32 v122, v126, v122
	v_mul_f32_e32 v120, v151, v120
	v_exp_f32_e32 v151, v126
	v_mul_f32_e32 v121, v124, v121
	v_exp_f32_e32 v124, v127
	v_cvt_pk_bf16_f32 v120, v120, v121
	v_add_f32_e32 v125, 1.0, v151
	v_rcp_f32_e32 v125, v125
	v_add_f32_e32 v124, 1.0, v124
	v_rcp_f32_e32 v124, v124
	v_mul_f32_e32 v123, v127, v123
	v_mul_f32_e32 v122, v125, v122
	v_exp_f32_e32 v125, v116
	v_mul_f32_e32 v112, v116, v112
	v_mul_f32_e32 v123, v124, v123
	v_mul_f32_e32 v113, v117, v113
	v_add_f32_e32 v121, 1.0, v125
	v_exp_f32_e32 v125, v117
	v_rcp_f32_e32 v124, v121
	v_cvt_pk_bf16_f32 v121, v122, v123
	v_exp_f32_e32 v122, v118
	v_add_f32_e32 v116, 1.0, v125
	v_rcp_f32_e32 v116, v116
	v_exp_f32_e32 v117, v119
	v_lshl_or_b32 v152, s84, 7, v146
	v_mul_f32_e32 v112, v124, v112
	v_mul_f32_e32 v113, v116, v113
	v_add_f32_e32 v116, 1.0, v122
	v_add_f32_e32 v117, 1.0, v117
	v_rcp_f32_e32 v116, v116
	v_rcp_f32_e32 v117, v117
	v_mul_f32_e32 v114, v118, v114
	v_mul_f32_e32 v115, v119, v115
	v_lshl_add_u32 v150, s50, 8, v144
	v_ashrrev_i32_e32 v153, 31, v152
	v_mul_f32_e32 v114, v116, v114
	v_mul_f32_e32 v115, v117, v115
	v_cvt_pk_bf16_f32 v122, v112, v113
	v_mov_b64_e32 v[112:113], s[26:27]
	v_cvt_pk_bf16_f32 v123, v114, v115
	v_mad_i64_i32 v[116:117], s[20:21], v150, s83, v[112:113]
	v_lshlrev_b64 v[114:115], 1, v[152:153]
	v_lshl_add_u64 v[116:117], v[116:117], 0, v[114:115]
	v_mov_b32_e32 v224, v120
	v_mov_b32_e32 v225, v121
	v_mov_b32_e32 v226, v122
	v_mov_b32_e32 v227, v123
	v_exp_f32_e32 v116, v109
	v_exp_f32_e32 v118, v108
	v_mul_f32_e32 v104, v108, v104
	v_mul_f32_e32 v105, v109, v105
	v_add_f32_e32 v108, 1.0, v116
	v_exp_f32_e32 v116, v110
	v_rcp_f32_e32 v108, v108
	v_add_f32_e32 v117, 1.0, v118
	v_rcp_f32_e32 v117, v117
	v_add_f32_e32 v109, 1.0, v116
	v_rcp_f32_e32 v109, v109
	v_mul_f32_e32 v106, v110, v106
	v_mul_f32_e32 v105, v108, v105
	v_exp_f32_e32 v108, v111
	v_mul_f32_e32 v106, v109, v106
	v_exp_f32_e32 v109, v100
	v_mul_f32_e32 v104, v117, v104
	v_add_f32_e32 v108, 1.0, v108
	v_cvt_pk_bf16_f32 v104, v104, v105
	v_add_f32_e32 v105, 1.0, v109
	v_exp_f32_e32 v109, v101
	v_rcp_f32_e32 v108, v108
	v_mul_f32_e32 v107, v111, v107
	v_mul_f32_e32 v96, v100, v96
	v_add_f32_e32 v100, 1.0, v109
	v_mul_f32_e32 v107, v108, v107
	v_rcp_f32_e32 v108, v105
	v_cvt_pk_bf16_f32 v105, v106, v107
	v_rcp_f32_e32 v100, v100
	v_exp_f32_e32 v106, v102
	v_mul_f32_e32 v97, v101, v97
	v_exp_f32_e32 v101, v103
	v_mul_f32_e32 v97, v100, v97
	v_add_f32_e32 v100, 1.0, v106
	v_mul_f32_e32 v96, v108, v96
	v_add_f32_e32 v101, 1.0, v101
	v_rcp_f32_e32 v100, v100
	v_rcp_f32_e32 v101, v101
	v_cvt_pk_bf16_f32 v106, v96, v97
	v_or_b32_e32 v96, 16, v150
	v_mad_i64_i32 v[96:97], s[20:21], v96, s83, v[112:113]
	v_mul_f32_e32 v98, v102, v98
	v_mul_f32_e32 v99, v103, v99
	v_lshl_add_u64 v[96:97], v[96:97], 0, v[114:115]
	v_mul_f32_e32 v98, v100, v98
	v_mul_f32_e32 v99, v101, v99
	v_cvt_pk_bf16_f32 v107, v98, v99
	v_mov_b32_e32 v228, v104
	v_mov_b32_e32 v229, v105
	v_mov_b32_e32 v230, v106
	v_mov_b32_e32 v231, v107
	v_exp_f32_e32 v96, v93
	v_exp_f32_e32 v98, v92
	v_mul_f32_e32 v88, v92, v88
	v_mul_f32_e32 v89, v93, v89
	v_add_f32_e32 v92, 1.0, v96
	v_exp_f32_e32 v96, v94
	v_rcp_f32_e32 v92, v92
	v_add_f32_e32 v97, 1.0, v98
	v_rcp_f32_e32 v97, v97
	v_add_f32_e32 v93, 1.0, v96
	v_rcp_f32_e32 v93, v93
	v_mul_f32_e32 v90, v94, v90
	v_mul_f32_e32 v89, v92, v89
	v_exp_f32_e32 v92, v95
	v_mul_f32_e32 v90, v93, v90
	v_exp_f32_e32 v93, v84
	v_mul_f32_e32 v88, v97, v88
	v_add_f32_e32 v92, 1.0, v92
	v_cvt_pk_bf16_f32 v88, v88, v89
	v_add_f32_e32 v89, 1.0, v93
	v_exp_f32_e32 v93, v85
	v_rcp_f32_e32 v92, v92
	v_mul_f32_e32 v91, v95, v91
	v_mul_f32_e32 v80, v84, v80
	v_add_f32_e32 v84, 1.0, v93
	v_mul_f32_e32 v91, v92, v91
	v_rcp_f32_e32 v92, v89
	v_cvt_pk_bf16_f32 v89, v90, v91
	v_rcp_f32_e32 v84, v84
	v_exp_f32_e32 v90, v86
	v_mul_f32_e32 v81, v85, v81
	v_exp_f32_e32 v85, v87
	v_mul_f32_e32 v81, v84, v81
	v_add_f32_e32 v84, 1.0, v90
	v_mul_f32_e32 v80, v92, v80
	v_add_f32_e32 v85, 1.0, v85
	v_rcp_f32_e32 v84, v84
	v_rcp_f32_e32 v85, v85
	v_cvt_pk_bf16_f32 v90, v80, v81
	v_or_b32_e32 v80, 32, v150
	v_mad_i64_i32 v[80:81], s[20:21], v80, s83, v[112:113]
	v_mul_f32_e32 v82, v86, v82
	v_mul_f32_e32 v83, v87, v83
	v_lshl_add_u64 v[80:81], v[80:81], 0, v[114:115]
	v_mul_f32_e32 v82, v84, v82
	v_mul_f32_e32 v83, v85, v83
	v_cvt_pk_bf16_f32 v91, v82, v83
	v_mov_b32_e32 v232, v88
	v_mov_b32_e32 v233, v89
	v_mov_b32_e32 v234, v90
	v_mov_b32_e32 v235, v91
	v_exp_f32_e32 v80, v77
	v_exp_f32_e32 v82, v76
	v_mul_f32_e32 v72, v76, v72
	v_mul_f32_e32 v73, v77, v73
	v_add_f32_e32 v76, 1.0, v80
	v_exp_f32_e32 v80, v78
	v_rcp_f32_e32 v76, v76
	v_add_f32_e32 v81, 1.0, v82
	v_rcp_f32_e32 v81, v81
	v_add_f32_e32 v77, 1.0, v80
	v_rcp_f32_e32 v77, v77
	v_mul_f32_e32 v74, v78, v74
	v_mul_f32_e32 v73, v76, v73
	v_exp_f32_e32 v76, v79
	v_mul_f32_e32 v74, v77, v74
	v_exp_f32_e32 v77, v68
	v_mul_f32_e32 v72, v81, v72
	v_add_f32_e32 v76, 1.0, v76
	v_cvt_pk_bf16_f32 v72, v72, v73
	v_add_f32_e32 v73, 1.0, v77
	v_exp_f32_e32 v77, v69
	v_rcp_f32_e32 v76, v76
	v_mul_f32_e32 v75, v79, v75
	v_mul_f32_e32 v64, v68, v64
	v_add_f32_e32 v68, 1.0, v77
	v_mul_f32_e32 v75, v76, v75
	v_rcp_f32_e32 v76, v73
	v_cvt_pk_bf16_f32 v73, v74, v75
	v_rcp_f32_e32 v68, v68
	v_exp_f32_e32 v74, v70
	v_mul_f32_e32 v65, v69, v65
	v_exp_f32_e32 v69, v71
	v_mul_f32_e32 v65, v68, v65
	v_add_f32_e32 v68, 1.0, v74
	v_mul_f32_e32 v64, v76, v64
	v_add_f32_e32 v69, 1.0, v69
	v_rcp_f32_e32 v68, v68
	v_rcp_f32_e32 v69, v69
	v_cvt_pk_bf16_f32 v74, v64, v65
	v_or_b32_e32 v64, 48, v150
	v_mad_i64_i32 v[64:65], s[20:21], v64, s83, v[112:113]
	v_mul_f32_e32 v66, v70, v66
	v_mul_f32_e32 v67, v71, v67
	v_lshl_add_u64 v[64:65], v[64:65], 0, v[114:115]
	v_mul_f32_e32 v66, v68, v66
	v_mul_f32_e32 v67, v69, v67
	v_cvt_pk_bf16_f32 v75, v66, v67
	v_mov_b32_e32 v236, v72
	v_mov_b32_e32 v237, v73
	v_mov_b32_e32 v238, v74
	v_mov_b32_e32 v239, v75
	v_exp_f32_e32 v65, v61
	v_exp_f32_e32 v66, v60
	v_mul_f32_e32 v56, v60, v56
	v_mul_f32_e32 v57, v61, v57
	v_add_f32_e32 v60, 1.0, v65
	v_exp_f32_e32 v65, v62
	v_rcp_f32_e32 v60, v60
	v_add_f32_e32 v66, 1.0, v66
	v_rcp_f32_e32 v66, v66
	v_add_f32_e32 v61, 1.0, v65
	v_rcp_f32_e32 v61, v61
	v_mul_f32_e32 v58, v62, v58
	v_mul_f32_e32 v57, v60, v57
	v_exp_f32_e32 v60, v63
	v_mul_f32_e32 v58, v61, v58
	v_exp_f32_e32 v61, v52
	v_mul_f32_e32 v56, v66, v56
	v_add_f32_e32 v60, 1.0, v60
	v_cvt_pk_bf16_f32 v56, v56, v57
	v_add_f32_e32 v57, 1.0, v61
	v_exp_f32_e32 v61, v53
	v_rcp_f32_e32 v60, v60
	v_mul_f32_e32 v59, v63, v59
	v_mul_f32_e32 v48, v52, v48
	v_add_f32_e32 v52, 1.0, v61
	v_mul_f32_e32 v59, v60, v59
	v_rcp_f32_e32 v60, v57
	v_cvt_pk_bf16_f32 v57, v58, v59
	v_rcp_f32_e32 v52, v52
	v_exp_f32_e32 v58, v54
	v_mul_f32_e32 v49, v53, v49
	v_exp_f32_e32 v53, v55
	v_mul_f32_e32 v49, v52, v49
	v_add_f32_e32 v52, 1.0, v58
	v_rcp_f32_e32 v52, v52
	v_add_f32_e32 v53, 1.0, v53
	v_rcp_f32_e32 v53, v53
	v_add_u32_e32 v64, 0x80, v150
	v_mul_f32_e32 v48, v60, v48
	v_cvt_pk_bf16_f32 v58, v48, v49
	v_mad_i64_i32 v[48:49], s[20:21], v64, s83, v[112:113]
	v_mul_f32_e32 v50, v54, v50
	v_mul_f32_e32 v51, v55, v51
	v_lshl_add_u64 v[48:49], v[48:49], 0, v[114:115]
	v_mul_f32_e32 v50, v52, v50
	v_mul_f32_e32 v51, v53, v51
	v_cvt_pk_bf16_f32 v59, v50, v51
	v_mov_b32_e32 v244, v56
	v_mov_b32_e32 v245, v57
	v_mov_b32_e32 v246, v58
	v_mov_b32_e32 v247, v59
	v_exp_f32_e32 v48, v45
	v_exp_f32_e32 v50, v44
	v_mul_f32_e32 v40, v44, v40
	v_mul_f32_e32 v41, v45, v41
	v_add_f32_e32 v44, 1.0, v48
	v_exp_f32_e32 v48, v46
	v_rcp_f32_e32 v44, v44
	v_add_f32_e32 v49, 1.0, v50
	v_rcp_f32_e32 v49, v49
	v_add_f32_e32 v45, 1.0, v48
	v_rcp_f32_e32 v45, v45
	v_mul_f32_e32 v42, v46, v42
	v_mul_f32_e32 v41, v44, v41
	v_exp_f32_e32 v44, v47
	v_mul_f32_e32 v42, v45, v42
	v_exp_f32_e32 v45, v36
	v_mul_f32_e32 v40, v49, v40
	v_add_f32_e32 v44, 1.0, v44
	v_cvt_pk_bf16_f32 v40, v40, v41
	v_add_f32_e32 v41, 1.0, v45
	v_exp_f32_e32 v45, v37
	v_rcp_f32_e32 v44, v44
	v_mul_f32_e32 v43, v47, v43
	v_mul_f32_e32 v32, v36, v32
	v_add_f32_e32 v36, 1.0, v45
	v_mul_f32_e32 v43, v44, v43
	v_rcp_f32_e32 v44, v41
	v_cvt_pk_bf16_f32 v41, v42, v43
	v_rcp_f32_e32 v36, v36
	v_exp_f32_e32 v42, v38
	v_mul_f32_e32 v33, v37, v33
	v_exp_f32_e32 v37, v39
	v_mul_f32_e32 v33, v36, v33
	v_add_f32_e32 v36, 1.0, v42
	v_mul_f32_e32 v32, v44, v32
	v_add_f32_e32 v37, 1.0, v37
	v_rcp_f32_e32 v36, v36
	v_rcp_f32_e32 v37, v37
	v_cvt_pk_bf16_f32 v42, v32, v33
	v_add_u32_e32 v32, 0x90, v150
	v_mad_i64_i32 v[32:33], s[20:21], v32, s83, v[112:113]
	v_mul_f32_e32 v34, v38, v34
	v_mul_f32_e32 v35, v39, v35
	v_lshl_add_u64 v[32:33], v[32:33], 0, v[114:115]
	v_mul_f32_e32 v34, v36, v34
	v_mul_f32_e32 v35, v37, v35
	v_cvt_pk_bf16_f32 v43, v34, v35
	v_mov_b32_e32 v248, v40
	v_mov_b32_e32 v249, v41
	v_mov_b32_e32 v250, v42
	v_mov_b32_e32 v251, v43
	v_exp_f32_e32 v32, v29
	v_exp_f32_e32 v34, v28
	v_mul_f32_e32 v24, v28, v24
	v_mul_f32_e32 v25, v29, v25
	v_add_f32_e32 v28, 1.0, v32
	v_exp_f32_e32 v32, v30
	v_rcp_f32_e32 v28, v28
	v_add_f32_e32 v33, 1.0, v34
	v_rcp_f32_e32 v33, v33
	v_add_f32_e32 v29, 1.0, v32
	v_rcp_f32_e32 v29, v29
	v_mul_f32_e32 v26, v30, v26
	v_mul_f32_e32 v25, v28, v25
	v_exp_f32_e32 v28, v31
	v_mul_f32_e32 v26, v29, v26
	v_exp_f32_e32 v29, v20
	v_mul_f32_e32 v24, v33, v24
	v_add_f32_e32 v28, 1.0, v28
	v_cvt_pk_bf16_f32 v24, v24, v25
	v_add_f32_e32 v25, 1.0, v29
	v_exp_f32_e32 v29, v21
	v_rcp_f32_e32 v28, v28
	v_mul_f32_e32 v27, v31, v27
	v_mul_f32_e32 v16, v20, v16
	v_add_f32_e32 v20, 1.0, v29
	v_mul_f32_e32 v27, v28, v27
	v_rcp_f32_e32 v28, v25
	v_cvt_pk_bf16_f32 v25, v26, v27
	v_rcp_f32_e32 v20, v20
	v_exp_f32_e32 v26, v22
	v_mul_f32_e32 v17, v21, v17
	v_exp_f32_e32 v21, v23
	v_mul_f32_e32 v17, v20, v17
	v_add_f32_e32 v20, 1.0, v26
	v_mul_f32_e32 v16, v28, v16
	v_add_f32_e32 v21, 1.0, v21
	v_rcp_f32_e32 v20, v20
	v_rcp_f32_e32 v21, v21
	v_cvt_pk_bf16_f32 v26, v16, v17
	v_add_u32_e32 v16, 0xa0, v150
	v_mad_i64_i32 v[16:17], s[20:21], v16, s83, v[112:113]
	v_mul_f32_e32 v18, v22, v18
	v_mul_f32_e32 v19, v23, v19
	v_lshl_add_u64 v[16:17], v[16:17], 0, v[114:115]
	v_mul_f32_e32 v18, v20, v18
	v_mul_f32_e32 v19, v21, v19
	v_cvt_pk_bf16_f32 v27, v18, v19
	v_mov_b32_e32 v216, v24
	v_mov_b32_e32 v217, v25
	v_mov_b32_e32 v218, v26
	v_mov_b32_e32 v219, v27
	v_exp_f32_e32 v16, v13
	v_exp_f32_e32 v18, v12
	v_mul_f32_e32 v8, v12, v8
	v_mul_f32_e32 v9, v13, v9
	v_add_f32_e32 v12, 1.0, v16
	v_exp_f32_e32 v16, v14
	v_rcp_f32_e32 v12, v12
	v_add_f32_e32 v17, 1.0, v18
	v_rcp_f32_e32 v17, v17
	v_add_f32_e32 v13, 1.0, v16
	v_rcp_f32_e32 v13, v13
	v_mul_f32_e32 v10, v14, v10
	v_mul_f32_e32 v9, v12, v9
	v_exp_f32_e32 v12, v15
	v_mul_f32_e32 v10, v13, v10
	v_exp_f32_e32 v13, v4
	v_mul_f32_e32 v8, v17, v8
	v_add_f32_e32 v12, 1.0, v12
	v_cvt_pk_bf16_f32 v8, v8, v9
	v_add_f32_e32 v9, 1.0, v13
	v_exp_f32_e32 v13, v5
	v_rcp_f32_e32 v12, v12
	v_mul_f32_e32 v11, v15, v11
	v_mul_f32_e32 v0, v4, v0
	v_add_f32_e32 v4, 1.0, v13
	v_mul_f32_e32 v11, v12, v11
	v_rcp_f32_e32 v12, v9
	v_cvt_pk_bf16_f32 v9, v10, v11
	v_rcp_f32_e32 v4, v4
	v_exp_f32_e32 v10, v6
	v_mul_f32_e32 v1, v5, v1
	v_exp_f32_e32 v5, v7
	v_mul_f32_e32 v1, v4, v1
	v_add_f32_e32 v4, 1.0, v10
	v_mul_f32_e32 v0, v12, v0
	v_add_f32_e32 v5, 1.0, v5
	v_rcp_f32_e32 v4, v4
	v_rcp_f32_e32 v5, v5
	v_cvt_pk_bf16_f32 v10, v0, v1
	v_add_u32_e32 v0, 0xb0, v150
	v_mad_i64_i32 v[0:1], s[20:21], v0, s83, v[112:113]
	v_mul_f32_e32 v2, v6, v2
	v_mul_f32_e32 v3, v7, v3
	v_lshl_add_u64 v[0:1], v[0:1], 0, v[114:115]
	s_andn2_b64 vcc, exec, s[0:1]
	s_mov_b64 s[0:1], -1
	v_mul_f32_e32 v2, v4, v2
	v_mul_f32_e32 v3, v5, v3
	v_cvt_pk_bf16_f32 v11, v2, v3
	v_mov_b32_e32 v220, v8
	v_mov_b32_e32 v221, v9
	v_mov_b32_e32 v222, v10
	v_mov_b32_e32 v223, v11
	s_cbranch_vccnz .LBB0_115
	s_andn2_b64 vcc, exec, s[4:5]
	s_cbranch_vccnz .LBB0_114
	s_barrier
	s_branch .LBB0_114
.LBB0_125:
	global_store_dwordx4 v255, v[224:227], s[98:99]
	s_add_u32 s98, s98, 0x16000
	s_addc_u32 s99, s99, 0
	global_store_dwordx4 v255, v[228:231], s[98:99]
	s_add_u32 s98, s98, 0x16000
	s_addc_u32 s99, s99, 0
	global_store_dwordx4 v255, v[232:235], s[98:99]
	s_add_u32 s98, s98, 0x16000
	s_addc_u32 s99, s99, 0
	global_store_dwordx4 v255, v[236:239], s[98:99]
	s_add_u32 s98, s98, 0x6e000
	s_addc_u32 s99, s99, 0
	global_store_dwordx4 v255, v[244:247], s[98:99]
	s_add_u32 s98, s98, 0x16000
	s_addc_u32 s99, s99, 0
	global_store_dwordx4 v255, v[248:251], s[98:99]
	s_add_u32 s98, s98, 0x16000
	s_addc_u32 s99, s99, 0
	global_store_dwordx4 v255, v[216:219], s[98:99]
	s_add_u32 s98, s98, 0x16000
	s_addc_u32 s99, s99, 0
	global_store_dwordx4 v255, v[220:223], s[98:99]
	s_waitcnt vmcnt(0)
	s_barrier

.LBB0_200:
	s_add_u32 s89, s56, 0x100
	v_mov_b32_e32 v0, 0
	s_addc_u32 s90, s57, 0
	s_mov_b32 s91, -2
	s_waitcnt lgkmcnt(0)
	v_mov_b32_e32 v1, 0
	v_mov_b64_e32 v[2:3], 0
	v_mov_b64_e32 v[4:5], 0
	v_mov_b64_e32 v[6:7], 0
	v_mov_b64_e32 v[8:9], 0
	v_mov_b64_e32 v[10:11], 0
	v_mov_b64_e32 v[12:13], 0
	v_mov_b64_e32 v[14:15], 0
	v_mov_b64_e32 v[16:17], 0
	v_mov_b64_e32 v[18:19], 0
	v_mov_b64_e32 v[20:21], 0
	v_mov_b64_e32 v[22:23], 0
	v_mov_b64_e32 v[24:25], 0
	v_mov_b64_e32 v[26:27], 0
	v_mov_b64_e32 v[28:29], 0
	v_mov_b64_e32 v[30:31], 0
	v_mov_b64_e32 v[32:33], 0
	v_mov_b64_e32 v[34:35], 0
	v_mov_b64_e32 v[36:37], 0
	v_mov_b64_e32 v[38:39], 0
	v_mov_b64_e32 v[40:41], 0
	v_mov_b64_e32 v[42:43], 0
	v_mov_b64_e32 v[44:45], 0
	v_mov_b64_e32 v[46:47], 0
	v_mov_b64_e32 v[48:49], 0
	v_mov_b64_e32 v[50:51], 0
	v_mov_b64_e32 v[52:53], 0
	v_mov_b64_e32 v[54:55], 0
	v_mov_b64_e32 v[56:57], 0
	v_mov_b64_e32 v[58:59], 0
	v_mov_b64_e32 v[60:61], 0
	v_mov_b64_e32 v[62:63], 0
	v_mov_b64_e32 v[64:65], 0
	v_mov_b64_e32 v[66:67], 0
	v_mov_b64_e32 v[68:69], 0
	v_mov_b64_e32 v[70:71], 0
	v_mov_b64_e32 v[72:73], 0
	v_mov_b64_e32 v[74:75], 0
	v_mov_b64_e32 v[76:77], 0
	v_mov_b64_e32 v[78:79], 0
	v_mov_b64_e32 v[80:81], 0
	v_mov_b64_e32 v[82:83], 0
	v_mov_b64_e32 v[84:85], 0
	v_mov_b64_e32 v[86:87], 0
	v_mov_b64_e32 v[88:89], 0
	v_mov_b64_e32 v[90:91], 0
	v_mov_b64_e32 v[92:93], 0
	v_mov_b64_e32 v[94:95], 0
	v_mov_b64_e32 v[96:97], 0
	v_mov_b64_e32 v[98:99], 0
	v_mov_b64_e32 v[100:101], 0
	v_mov_b64_e32 v[102:103], 0
	v_mov_b64_e32 v[104:105], 0
	v_mov_b64_e32 v[106:107], 0
	v_mov_b64_e32 v[108:109], 0
	v_mov_b64_e32 v[110:111], 0
	v_mov_b64_e32 v[112:113], 0
	v_mov_b64_e32 v[114:115], 0
	v_mov_b64_e32 v[116:117], 0
	v_mov_b64_e32 v[118:119], 0
	v_mov_b64_e32 v[120:121], 0
	v_mov_b64_e32 v[122:123], 0
	v_mov_b64_e32 v[124:125], 0
	v_mov_b64_e32 v[126:127], 0

.LBB0_286:
	s_ashr_i32 s19, s18, 31
	s_lshl_b64 s[20:21], s[18:19], 19
	s_add_u32 s52, s24, s20
	s_addc_u32 s53, s25, s21
	s_and_b64 s[20:21], s[4:5], exec
	s_cselect_b32 s7, s53, s59
	s_cselect_b32 s19, s52, s58
	s_ashr_i32 s17, s16, 31
	s_lshl_b64 s[20:21], s[16:17], 19
	s_add_u32 s54, s10, s20
	s_addc_u32 s55, s11, s21
	s_and_b64 s[20:21], s[4:5], exec
	s_cselect_b32 s17, s55, s61
	s_cselect_b32 s57, s54, s60
	s_add_u32 s58, s58, 0x40080
	s_addc_u32 s59, s59, 0
	s_add_u32 s95, s60, 0x100
	v_mov_b32_e32 v0, 0
	s_addc_u32 s96, s61, 0
	s_mov_b32 s97, -2
	v_mov_b32_e32 v1, 0
	v_mov_b64_e32 v[2:3], 0
	v_mov_b64_e32 v[4:5], 0
	v_mov_b64_e32 v[6:7], 0
	v_mov_b64_e32 v[8:9], 0
	v_mov_b64_e32 v[10:11], 0
	v_mov_b64_e32 v[12:13], 0
	v_mov_b64_e32 v[14:15], 0
	v_mov_b64_e32 v[16:17], 0
	v_mov_b64_e32 v[18:19], 0
	v_mov_b64_e32 v[20:21], 0
	v_mov_b64_e32 v[22:23], 0
	v_mov_b64_e32 v[24:25], 0
	v_mov_b64_e32 v[26:27], 0
	v_mov_b64_e32 v[28:29], 0
	v_mov_b64_e32 v[30:31], 0
	v_mov_b64_e32 v[32:33], 0
	v_mov_b64_e32 v[34:35], 0
	v_mov_b64_e32 v[36:37], 0
	v_mov_b64_e32 v[38:39], 0
	v_mov_b64_e32 v[40:41], 0
	v_mov_b64_e32 v[42:43], 0
	v_mov_b64_e32 v[44:45], 0
	v_mov_b64_e32 v[46:47], 0
	v_mov_b64_e32 v[48:49], 0
	v_mov_b64_e32 v[50:51], 0
	v_mov_b64_e32 v[52:53], 0
	v_mov_b64_e32 v[54:55], 0
	v_mov_b64_e32 v[56:57], 0
	v_mov_b64_e32 v[58:59], 0
	v_mov_b64_e32 v[60:61], 0
	v_mov_b64_e32 v[62:63], 0
	v_mov_b64_e32 v[64:65], 0
	v_mov_b64_e32 v[66:67], 0
	v_mov_b64_e32 v[68:69], 0
	v_mov_b64_e32 v[70:71], 0
	v_mov_b64_e32 v[72:73], 0
	v_mov_b64_e32 v[74:75], 0
	v_mov_b64_e32 v[76:77], 0
	v_mov_b64_e32 v[78:79], 0
	v_mov_b64_e32 v[80:81], 0
	v_mov_b64_e32 v[82:83], 0
	v_mov_b64_e32 v[84:85], 0
	v_mov_b64_e32 v[86:87], 0
	v_mov_b64_e32 v[88:89], 0
	v_mov_b64_e32 v[90:91], 0
	v_mov_b64_e32 v[92:93], 0
	v_mov_b64_e32 v[94:95], 0
	v_mov_b64_e32 v[96:97], 0
	v_mov_b64_e32 v[98:99], 0
	v_mov_b64_e32 v[100:101], 0
	v_mov_b64_e32 v[102:103], 0
	v_mov_b64_e32 v[104:105], 0
	v_mov_b64_e32 v[106:107], 0
	v_mov_b64_e32 v[108:109], 0
	v_mov_b64_e32 v[110:111], 0
	v_mov_b64_e32 v[112:113], 0
	v_mov_b64_e32 v[114:115], 0
	v_mov_b64_e32 v[116:117], 0
	v_mov_b64_e32 v[118:119], 0
	v_mov_b64_e32 v[120:121], 0
	v_mov_b64_e32 v[122:123], 0
	v_mov_b64_e32 v[124:125], 0
	v_mov_b64_e32 v[126:127], 0

.LBB0_636:
	s_ashr_i32 s19, s18, 31
	s_lshl_b64 s[20:21], s[18:19], 19
	s_add_u32 s38, s36, s20
	s_addc_u32 s39, s37, s21
	s_and_b64 s[20:21], s[6:7], exec
	s_cselect_b32 s19, s39, s45
	s_cselect_b32 s43, s38, s44
	s_ashr_i32 s17, s16, 31
	s_lshl_b64 s[20:21], s[16:17], 19
	s_add_u32 s40, s72, s20
	s_addc_u32 s41, s73, s21
	s_and_b64 s[20:21], s[6:7], exec
	s_cselect_b32 s17, s41, s49
	s_cselect_b32 s66, s40, s48
	s_add_u32 s44, s44, 0x40080
	s_addc_u32 s45, s45, 0
	s_add_u32 s67, s48, 0x100
	v_mov_b32_e32 v0, 0
	s_addc_u32 s74, s49, 0
	s_mov_b32 s75, -2
	v_mov_b32_e32 v1, 0
	v_mov_b64_e32 v[2:3], 0
	v_mov_b64_e32 v[4:5], 0
	v_mov_b64_e32 v[6:7], 0
	v_mov_b64_e32 v[8:9], 0
	v_mov_b64_e32 v[10:11], 0
	v_mov_b64_e32 v[12:13], 0
	v_mov_b64_e32 v[14:15], 0
	v_mov_b64_e32 v[16:17], 0
	v_mov_b64_e32 v[18:19], 0
	v_mov_b64_e32 v[20:21], 0
	v_mov_b64_e32 v[22:23], 0
	v_mov_b64_e32 v[24:25], 0
	v_mov_b64_e32 v[26:27], 0
	v_mov_b64_e32 v[28:29], 0
	v_mov_b64_e32 v[30:31], 0
	v_mov_b64_e32 v[32:33], 0
	v_mov_b64_e32 v[34:35], 0
	v_mov_b64_e32 v[36:37], 0
	v_mov_b64_e32 v[38:39], 0
	v_mov_b64_e32 v[40:41], 0
	v_mov_b64_e32 v[42:43], 0
	v_mov_b64_e32 v[44:45], 0
	v_mov_b64_e32 v[46:47], 0
	v_mov_b64_e32 v[48:49], 0
	v_mov_b64_e32 v[50:51], 0
	v_mov_b64_e32 v[52:53], 0
	v_mov_b64_e32 v[54:55], 0
	v_mov_b64_e32 v[56:57], 0
	v_mov_b64_e32 v[58:59], 0
	v_mov_b64_e32 v[60:61], 0
	v_mov_b64_e32 v[62:63], 0
	v_mov_b64_e32 v[64:65], 0
	v_mov_b64_e32 v[66:67], 0
	v_mov_b64_e32 v[68:69], 0
	v_mov_b64_e32 v[70:71], 0
	v_mov_b64_e32 v[72:73], 0
	v_mov_b64_e32 v[74:75], 0
	v_mov_b64_e32 v[76:77], 0
	v_mov_b64_e32 v[78:79], 0
	v_mov_b64_e32 v[80:81], 0
	v_mov_b64_e32 v[82:83], 0
	v_mov_b64_e32 v[84:85], 0
	v_mov_b64_e32 v[86:87], 0
	v_mov_b64_e32 v[88:89], 0
	v_mov_b64_e32 v[90:91], 0
	v_mov_b64_e32 v[92:93], 0
	v_mov_b64_e32 v[94:95], 0
	v_mov_b64_e32 v[96:97], 0
	v_mov_b64_e32 v[98:99], 0
	v_mov_b64_e32 v[100:101], 0
	v_mov_b64_e32 v[102:103], 0
	v_mov_b64_e32 v[104:105], 0
	v_mov_b64_e32 v[106:107], 0
	v_mov_b64_e32 v[108:109], 0
	v_mov_b64_e32 v[110:111], 0
	v_mov_b64_e32 v[120:121], 0
	v_mov_b64_e32 v[122:123], 0
	v_mov_b64_e32 v[136:137], 0
	v_mov_b64_e32 v[138:139], 0
	v_mov_b64_e32 v[148:149], 0
	v_mov_b64_e32 v[150:151], 0
	v_mov_b64_e32 v[156:157], 0
	v_mov_b64_e32 v[158:159], 0

.LBB0_720:
	s_ashr_i32 s13, s12, 31
	s_lshl_b64 s[14:15], s[12:13], 19
	s_add_u32 s14, s24, s14
	s_addc_u32 s15, s25, s15
	s_and_b64 s[16:17], s[4:5], exec
	s_cselect_b32 s13, s15, s37
	s_cselect_b32 s57, s14, s36
	s_ashr_i32 s1, s0, 31
	s_lshl_b64 s[16:17], s[0:1], 19
	s_add_u32 s16, s70, s16
	s_addc_u32 s17, s71, s17
	s_and_b64 s[20:21], s[4:5], exec
	s_cselect_b32 s1, s17, s39
	s_cselect_b32 s58, s16, s38
	s_add_u32 s36, s36, 0x40080
	s_addc_u32 s37, s37, 0
	s_add_u32 s59, s38, 0x100
	v_mov_b32_e32 v0, 0
	s_addc_u32 s60, s39, 0
	s_mov_b32 s61, -2
	v_mov_b32_e32 v1, 0
	v_mov_b64_e32 v[2:3], 0
	v_mov_b64_e32 v[4:5], 0
	v_mov_b64_e32 v[6:7], 0
	v_mov_b64_e32 v[8:9], 0
	v_mov_b64_e32 v[10:11], 0
	v_mov_b64_e32 v[12:13], 0
	v_mov_b64_e32 v[14:15], 0
	v_mov_b64_e32 v[16:17], 0
	v_mov_b64_e32 v[18:19], 0
	v_mov_b64_e32 v[20:21], 0
	v_mov_b64_e32 v[22:23], 0
	v_mov_b64_e32 v[24:25], 0
	v_mov_b64_e32 v[26:27], 0
	v_mov_b64_e32 v[28:29], 0
	v_mov_b64_e32 v[30:31], 0
	v_mov_b64_e32 v[32:33], 0
	v_mov_b64_e32 v[34:35], 0
	v_mov_b64_e32 v[36:37], 0
	v_mov_b64_e32 v[38:39], 0
	v_mov_b64_e32 v[40:41], 0
	v_mov_b64_e32 v[42:43], 0
	v_mov_b64_e32 v[44:45], 0
	v_mov_b64_e32 v[46:47], 0
	v_mov_b64_e32 v[48:49], 0
	v_mov_b64_e32 v[50:51], 0
	v_mov_b64_e32 v[52:53], 0
	v_mov_b64_e32 v[54:55], 0
	v_mov_b64_e32 v[56:57], 0
	v_mov_b64_e32 v[58:59], 0
	v_mov_b64_e32 v[60:61], 0
	v_mov_b64_e32 v[62:63], 0
	v_mov_b64_e32 v[64:65], 0
	v_mov_b64_e32 v[66:67], 0
	v_mov_b64_e32 v[68:69], 0
	v_mov_b64_e32 v[70:71], 0
	v_mov_b64_e32 v[72:73], 0
	v_mov_b64_e32 v[74:75], 0
	v_mov_b64_e32 v[76:77], 0
	v_mov_b64_e32 v[78:79], 0
	v_mov_b64_e32 v[80:81], 0
	v_mov_b64_e32 v[82:83], 0
	v_mov_b64_e32 v[84:85], 0
	v_mov_b64_e32 v[86:87], 0
	v_mov_b64_e32 v[88:89], 0
	v_mov_b64_e32 v[90:91], 0
	v_mov_b64_e32 v[92:93], 0
	v_mov_b64_e32 v[94:95], 0
	v_mov_b64_e32 v[96:97], 0
	v_mov_b64_e32 v[98:99], 0
	v_mov_b64_e32 v[100:101], 0
	v_mov_b64_e32 v[102:103], 0
	v_mov_b64_e32 v[104:105], 0
	v_mov_b64_e32 v[106:107], 0
	v_mov_b64_e32 v[108:109], 0
	v_mov_b64_e32 v[110:111], 0
	v_mov_b64_e32 v[112:113], 0
	v_mov_b64_e32 v[114:115], 0
	v_mov_b64_e32 v[116:117], 0
	v_mov_b64_e32 v[118:119], 0
	v_mov_b64_e32 v[120:121], 0
	v_mov_b64_e32 v[122:123], 0
	v_mov_b64_e32 v[124:125], 0
	v_mov_b64_e32 v[126:127], 0

.LBB0_800:
	s_add_u32 s45, s16, 0x100
	v_mov_b32_e32 v0, 0
	s_addc_u32 s46, s17, 0
	s_mov_b32 s47, -2
	v_mov_b32_e32 v1, 0
	v_mov_b64_e32 v[2:3], 0
	v_mov_b64_e32 v[4:5], 0
	v_mov_b64_e32 v[6:7], 0
	v_mov_b64_e32 v[8:9], 0
	v_mov_b64_e32 v[10:11], 0
	v_mov_b64_e32 v[12:13], 0
	v_mov_b64_e32 v[14:15], 0
	v_mov_b64_e32 v[16:17], 0
	v_mov_b64_e32 v[18:19], 0
	v_mov_b64_e32 v[20:21], 0
	v_mov_b64_e32 v[22:23], 0
	v_mov_b64_e32 v[24:25], 0
	v_mov_b64_e32 v[26:27], 0
	v_mov_b64_e32 v[28:29], 0
	v_mov_b64_e32 v[30:31], 0
	v_mov_b64_e32 v[32:33], 0
	v_mov_b64_e32 v[34:35], 0
	v_mov_b64_e32 v[36:37], 0
	v_mov_b64_e32 v[38:39], 0
	v_mov_b64_e32 v[40:41], 0
	v_mov_b64_e32 v[42:43], 0
	v_mov_b64_e32 v[44:45], 0
	v_mov_b64_e32 v[46:47], 0
	v_mov_b64_e32 v[48:49], 0
	v_mov_b64_e32 v[50:51], 0
	v_mov_b64_e32 v[52:53], 0
	v_mov_b64_e32 v[54:55], 0
	v_mov_b64_e32 v[56:57], 0
	v_mov_b64_e32 v[58:59], 0
	v_mov_b64_e32 v[60:61], 0
	v_mov_b64_e32 v[62:63], 0
	v_mov_b64_e32 v[64:65], 0
	v_mov_b64_e32 v[66:67], 0
	v_mov_b64_e32 v[68:69], 0
	v_mov_b64_e32 v[70:71], 0
	v_mov_b64_e32 v[72:73], 0
	v_mov_b64_e32 v[74:75], 0
	v_mov_b64_e32 v[76:77], 0
	v_mov_b64_e32 v[78:79], 0
	v_mov_b64_e32 v[80:81], 0
	v_mov_b64_e32 v[82:83], 0
	v_mov_b64_e32 v[84:85], 0
	v_mov_b64_e32 v[86:87], 0
	v_mov_b64_e32 v[88:89], 0
	v_mov_b64_e32 v[90:91], 0
	v_mov_b64_e32 v[92:93], 0
	v_mov_b64_e32 v[94:95], 0
	v_mov_b64_e32 v[96:97], 0
	v_mov_b64_e32 v[98:99], 0
	v_mov_b64_e32 v[100:101], 0
	v_mov_b64_e32 v[102:103], 0
	v_mov_b64_e32 v[104:105], 0
	v_mov_b64_e32 v[106:107], 0
	v_mov_b64_e32 v[108:109], 0
	v_mov_b64_e32 v[110:111], 0
	v_mov_b64_e32 v[112:113], 0
	v_mov_b64_e32 v[114:115], 0
	v_mov_b64_e32 v[116:117], 0
	v_mov_b64_e32 v[118:119], 0
	v_mov_b64_e32 v[120:121], 0
	v_mov_b64_e32 v[122:123], 0
	v_mov_b64_e32 v[124:125], 0
	v_mov_b64_e32 v[126:127], 0

	.amdhsa_kernel _Z8mega_fwd4Args
		.amdhsa_group_segment_fixed_size 0
		.amdhsa_private_segment_fixed_size 0
		.amdhsa_kernarg_size 416
		.amdhsa_user_sgpr_count 2
		.amdhsa_user_sgpr_dispatch_ptr 0
		.amdhsa_user_sgpr_queue_ptr 0
		.amdhsa_user_sgpr_kernarg_segment_ptr 1
		.amdhsa_user_sgpr_dispatch_id 0
		.amdhsa_user_sgpr_kernarg_preload_length 0
		.amdhsa_user_sgpr_kernarg_preload_offset 0
		.amdhsa_user_sgpr_private_segment_size 0
		.amdhsa_uses_dynamic_stack 0
		.amdhsa_enable_private_segment 0
		.amdhsa_system_sgpr_workgroup_id_x 1
		.amdhsa_system_sgpr_workgroup_id_y 0
		.amdhsa_system_sgpr_workgroup_id_z 0
		.amdhsa_system_sgpr_workgroup_info 0
		.amdhsa_system_vgpr_workitem_id 2
		.amdhsa_next_free_vgpr 256
		.amdhsa_next_free_sgpr 102
		.amdhsa_accum_offset 256
		.amdhsa_reserve_vcc 1
		.amdhsa_float_round_mode_32 0
		.amdhsa_float_round_mode_16_64 0
		.amdhsa_float_denorm_mode_32 3
		.amdhsa_float_denorm_mode_16_64 3
		.amdhsa_dx10_clamp 1
		.amdhsa_ieee_mode 1
		.amdhsa_fp16_overflow 0
		.amdhsa_tg_split 0
		.amdhsa_exception_fp_ieee_invalid_op 0
		.amdhsa_exception_fp_denorm_src 0
		.amdhsa_exception_fp_ieee_div_zero 0
		.amdhsa_exception_fp_ieee_overflow 0
		.amdhsa_exception_fp_ieee_underflow 0
		.amdhsa_exception_fp_ieee_inexact 0
		.amdhsa_exception_int_div_zero 0
	.end_amdhsa_kernel

amdhsa.kernels:
  - .agpr_count:     0
    .args:
      - .offset:         0
        .size:           160
        .value_kind:     by_value
      - .offset:         160
        .size:           4
        .value_kind:     hidden_block_count_x
      - .offset:         164
        .size:           4
        .value_kind:     hidden_block_count_y
      - .offset:         168
        .size:           4
        .value_kind:     hidden_block_count_z
      - .offset:         172
        .size:           2
        .value_kind:     hidden_group_size_x
      - .offset:         174
        .size:           2
        .value_kind:     hidden_group_size_y
      - .offset:         176
        .size:           2
        .value_kind:     hidden_group_size_z
      - .offset:         178
        .size:           2
        .value_kind:     hidden_remainder_x
      - .offset:         180
        .size:           2
        .value_kind:     hidden_remainder_y
      - .offset:         182
        .size:           2
        .value_kind:     hidden_remainder_z
      - .offset:         200
        .size:           8
        .value_kind:     hidden_global_offset_x
      - .offset:         208
        .size:           8
        .value_kind:     hidden_global_offset_y
      - .offset:         216
        .size:           8
        .value_kind:     hidden_global_offset_z
      - .offset:         224
        .size:           2
        .value_kind:     hidden_grid_dims
      - .offset:         248
        .size:           8
        .value_kind:     hidden_multigrid_sync_arg
      - .offset:         280
        .size:           4
        .value_kind:     hidden_dynamic_lds_size
    .group_segment_fixed_size: 0
    .kernarg_segment_align: 8
    .kernarg_segment_size: 416
    .language:       OpenCL C
    .language_version:
      - 2
      - 0
    .max_flat_workgroup_size: 512
    .name:           _Z8mega_fwd4Args
    .private_segment_fixed_size: 0
    .sgpr_count:     108
    .sgpr_spill_count: 4
    .symbol:         _Z8mega_fwd4Args.kd
    .uniform_work_group_size: 1
    .uses_dynamic_stack: false
    .vgpr_count:     256
    .vgpr_spill_count: 0
    .wavefront_size: 64
